# indexer tile ring reduced to two buffers per wave (8 loads in flight instead of 16): less L2 queueing
# speedup vs baseline: 1.0011x; 1.0011x over previous
.LBB0_694:
	s_or_b64 exec, exec, s[6:7]
	v_cmp_gt_i32_e64 s[8:9], 4, v144
	s_and_saveexec_b64 s[6:7], s[8:9]
	s_cbranch_execz .LBB0_696
	v_lshl_add_u32 v1, v144, 5, 0
	v_add_u32_e32 v1, 0x25800, v1
	ds_write_b128 v1, v[64:67]
	ds_write2_b32 v1, v2, v2 offset0:5 offset1:6
	v_mov_b32_e32 v3, 16
	ds_write_b32 v1, v3 offset:512
.LBB0_696:
	s_or_b64 exec, exec, s[6:7]
	s_add_i32 s6, s52, 3
	s_ashr_i32 s13, s6, 5
	s_ashr_i32 s51, s50, 31
	s_and_b32 s14, s13, 0xffffffe0
	s_add_i32 s10, s14, 32
	s_ashr_i32 s53, s60, 6
	s_lshl_b64 s[6:7], s[50:51], 20
	v_and_b32_e32 v145, 63, v144
	v_bfe_u32 v162, v144, 5, 1
	s_add_u32 s6, s40, s6
	v_lshlrev_b32_e32 v163, 1, v162
	s_addc_u32 s7, s41, s7
	v_lshlrev_b32_e32 v132, 4, v145
	v_and_b32_e32 v164, 31, v144
	v_lshlrev_b32_e32 v167, 16, v162
	v_lshl_add_u32 v165, v162, 13, s68
	v_add_u32_e32 v1, s52, v163
	v_lshl_add_u64 v[156:157], s[6:7], 0, v[132:133]
	v_lshl_add_u32 v166, v145, 2, s71
	s_waitcnt lgkmcnt(0)
	s_barrier
	s_min_i32 s6, s53, s13
	s_ashr_i32 s7, s6, 31
	s_lshl_b64 s[6:7], s[6:7], 12
	v_lshl_add_u64 v[4:5], v[156:157], 0, s[6:7]
	global_load_dwordx4 v[80:83], v[4:5], off
	global_load_dwordx4 v[76:79], v[4:5], off offset:1024
	global_load_dwordx4 v[72:75], v[4:5], off offset:2048
	global_load_dwordx4 v[68:71], v[4:5], off offset:3072
	s_add_i32 s6, s53, 8
	s_min_i32 s6, s6, s13
	s_ashr_i32 s7, s6, 31
	s_lshl_b64 s[6:7], s[6:7], 12
	v_lshl_add_u64 v[4:5], v[156:157], 0, s[6:7]
	global_load_dwordx4 v[96:99], v[4:5], off
	global_load_dwordx4 v[92:95], v[4:5], off offset:1024
	global_load_dwordx4 v[88:91], v[4:5], off offset:2048
	global_load_dwordx4 v[84:87], v[4:5], off offset:3072
	s_waitcnt vmcnt(8)
	v_swap_b32 v135, v36
	v_swap_b32 v137, v38
	v_swap_b32 v139, v40
	v_swap_b32 v141, v42
	v_add_u32_e32 v132, 1, v1
	v_lshlrev_b32_e32 v168, 2, v164
	v_mov_b32_e32 v172, 0x25a00
	s_mov_b32 s16, s53
	s_add_i32 s17, s53, 8
	s_mov_b32 s10, 0
	v_add_u32_e32 v175, v167, v168
	s_mov_b64 exec, 1
	ds_add_rtn_u32 v171, v172, v149
	s_mov_b64 exec, -1
	s_waitcnt lgkmcnt(0)
	v_readfirstlane_b32 s15, v171
	s_mov_b32 s14, -1
	s_branch .Lidx_entry0
.Lidx_loop:
	s_mov_b32 s14, s17
	s_mov_b32 s17, s15
	s_mov_b64 exec, 1
	ds_add_rtn_u32 v171, v172, v149
	s_mov_b64 exec, -1
	s_min_i32 s6, s17, s13
	s_ashr_i32 s7, s6, 31
	s_lshl_b64 s[6:7], s[6:7], 12
	s_waitcnt vmcnt(4)
	v_lshl_add_u64 v[84:85], v[156:157], 0, s[6:7]
	global_load_dwordx4 v[96:99], v[84:85], off
	global_load_dwordx4 v[92:95], v[84:85], off offset:1024
	global_load_dwordx4 v[88:91], v[84:85], off offset:2048
	s_nop 0
	global_load_dwordx4 v[84:87], v[84:85], off offset:3072
.Lidx_entry0:
	s_cmp_gt_i32 s16, s13
	s_cbranch_scc1 .Lidx_exit_prev1
	s_waitcnt vmcnt(7)
	v_mfma_f32_32x32x16_bf16 v[20:35], v[44:47], v[80:83], 0
	s_waitcnt vmcnt(6)
	v_mfma_f32_32x32x16_bf16 v[20:35], v[48:51], v[76:79], v[20:35]
	s_waitcnt vmcnt(5)
	v_mfma_f32_32x32x16_bf16 v[20:35], v[52:55], v[72:75], v[20:35]
	s_waitcnt vmcnt(4)
	v_mfma_f32_32x32x16_bf16 v[20:35], v[56:59], v[68:71], v[20:35]
	s_cmp_lt_i32 s14, 0
	s_cbranch_scc1 .Lidx_nopost0
	v_max_i32_e32 v177, 0, v4
	v_max_i32_e32 v176, 0, v12
	v_max_i32_e32 v179, 0, v5
	v_pk_fma_f32 v[176:177], v[134:135], v[176:177], 0 op_sel_hi:[1,1,0]
	v_max_i32_e32 v178, 0, v13
	v_max_i32_e32 v181, 0, v6
	v_max_i32_e32 v180, 0, v14
	v_pk_fma_f32 v[176:177], v[36:37], v[178:179], v[176:177]
	v_lshl_or_b32 v188, s14, 5, v164
	v_pk_fma_f32 v[176:177], v[136:137], v[180:181], v[176:177]
	v_max_i32_e32 v179, 0, v7
	v_max_i32_e32 v178, 0, v15
	v_pk_fma_f32 v[176:177], v[38:39], v[178:179], v[176:177]
	v_max_i32_e32 v179, 0, v8
	v_max_i32_e32 v178, 0, v16
	v_pk_fma_f32 v[176:177], v[138:139], v[178:179], v[176:177]
	v_max_i32_e32 v179, 0, v9
	v_max_i32_e32 v178, 0, v17
	v_pk_fma_f32 v[176:177], v[40:41], v[178:179], v[176:177]
	v_max_i32_e32 v179, 0, v10
	v_max_i32_e32 v178, 0, v18
	v_pk_fma_f32 v[176:177], v[140:141], v[178:179], v[176:177]
	v_max_i32_e32 v179, 0, v11
	v_max_i32_e32 v178, 0, v19
	v_pk_fma_f32 v[176:177], v[42:43], v[178:179], v[176:177]
	s_nop 0
	v_and_b32_e32 v183, 0x7fffffff, v177
	v_and_b32_e32 v182, 0x7fffffff, v176
	v_xor_b32_e32 v185, -1, v177
	v_pk_add_f32 v[182:183], v[182:183], 0 neg_lo:[1,1] neg_hi:[1,1]
	v_cmp_gt_i32_e32 vcc, 0, v177
	v_xor_b32_e32 v184, -1, v176
	s_nop 0
	v_cndmask_b32_e32 v186, v183, v185, vcc
	v_cmp_gt_i32_e32 vcc, 0, v176
	s_nop 1
	v_cndmask_b32_e32 v187, v182, v184, vcc
	v_cmp_le_i32_e32 vcc, v188, v132
	s_nop 1
	v_cndmask_b32_e32 v187, 0, v187, vcc
	v_cmp_le_i32_e32 vcc, v188, v1
	v_lshl_add_u32 v189, s14, 7, v175
	s_nop 0
	v_cndmask_b32_e32 v186, 0, v186, vcc
	ds_write2st64_b32 v189, v186, v187 offset1:128
	v_lshrrev_b32_e32 v190, 20, v186
	v_cmp_eq_u32_e32 vcc, 0, v186
	v_lshrrev_b32_e32 v191, 17, v186
	v_and_b32_e32 v190, 0xffc, v190
	v_and_b32_e32 v191, 16, v191
	v_add_u32_e32 v190, v165, v190
	v_lshlrev_b32_e64 v191, v191, 1
	v_cndmask_b32_e32 v190, v190, v166, vcc
	v_cndmask_b32_e64 v191, v191, 0, vcc
	ds_add_u32 v190, v191
	v_lshrrev_b32_e32 v190, 20, v187
	v_cmp_eq_u32_e32 vcc, 0, v187
	v_lshrrev_b32_e32 v191, 17, v187
	v_and_b32_e32 v190, 0xffc, v190
	v_and_b32_e32 v191, 16, v191
	v_add3_u32 v190, v165, v190, s73
	v_lshlrev_b32_e64 v191, v191, 1
	v_cndmask_b32_e32 v190, v190, v166, vcc
	v_cndmask_b32_e64 v191, v191, 0, vcc
	ds_add_u32 v190, v191
	s_waitcnt lgkmcnt(3)
	s_branch .Lidx_join0

.Lidx_join0:
	v_readfirstlane_b32 s15, v171
	s_mov_b32 s14, s16
	s_mov_b32 s16, s15
	s_mov_b64 exec, 1
	ds_add_rtn_u32 v171, v172, v149
	s_mov_b64 exec, -1
	s_min_i32 s6, s16, s13
	s_ashr_i32 s7, s6, 31
	s_lshl_b64 s[6:7], s[6:7], 12
	s_waitcnt vmcnt(4)
	v_lshl_add_u64 v[68:69], v[156:157], 0, s[6:7]
	global_load_dwordx4 v[80:83], v[68:69], off
	global_load_dwordx4 v[76:79], v[68:69], off offset:1024
	global_load_dwordx4 v[72:75], v[68:69], off offset:2048
	s_nop 0
	global_load_dwordx4 v[68:71], v[68:69], off offset:3072
	s_cmp_gt_i32 s17, s13
	s_cbranch_scc1 .Lidx_exit_prev0
	s_waitcnt vmcnt(7)
	v_mfma_f32_32x32x16_bf16 v[4:19], v[44:47], v[96:99], 0
	s_waitcnt vmcnt(6)
	v_mfma_f32_32x32x16_bf16 v[4:19], v[48:51], v[92:95], v[4:19]
	s_waitcnt vmcnt(5)
	v_mfma_f32_32x32x16_bf16 v[4:19], v[52:55], v[88:91], v[4:19]
	s_waitcnt vmcnt(4)
	v_mfma_f32_32x32x16_bf16 v[4:19], v[56:59], v[84:87], v[4:19]
	v_max_i32_e32 v177, 0, v20
	v_max_i32_e32 v176, 0, v28
	v_max_i32_e32 v179, 0, v21
	v_pk_fma_f32 v[176:177], v[134:135], v[176:177], 0 op_sel_hi:[1,1,0]
	v_max_i32_e32 v178, 0, v29
	v_max_i32_e32 v181, 0, v22
	v_max_i32_e32 v180, 0, v30
	v_pk_fma_f32 v[176:177], v[36:37], v[178:179], v[176:177]
	v_lshl_or_b32 v188, s14, 5, v164
	v_pk_fma_f32 v[176:177], v[136:137], v[180:181], v[176:177]
	v_max_i32_e32 v179, 0, v23
	v_max_i32_e32 v178, 0, v31
	v_pk_fma_f32 v[176:177], v[38:39], v[178:179], v[176:177]
	v_max_i32_e32 v179, 0, v24
	v_max_i32_e32 v178, 0, v32
	v_pk_fma_f32 v[176:177], v[138:139], v[178:179], v[176:177]
	v_max_i32_e32 v179, 0, v25
	v_max_i32_e32 v178, 0, v33
	v_pk_fma_f32 v[176:177], v[40:41], v[178:179], v[176:177]
	v_max_i32_e32 v179, 0, v26
	v_max_i32_e32 v178, 0, v34
	v_pk_fma_f32 v[176:177], v[140:141], v[178:179], v[176:177]
	v_max_i32_e32 v179, 0, v27
	v_max_i32_e32 v178, 0, v35
	v_pk_fma_f32 v[176:177], v[42:43], v[178:179], v[176:177]
	s_nop 0
	v_and_b32_e32 v183, 0x7fffffff, v177
	v_and_b32_e32 v182, 0x7fffffff, v176
	v_xor_b32_e32 v185, -1, v177
	v_pk_add_f32 v[182:183], v[182:183], 0 neg_lo:[1,1] neg_hi:[1,1]
	v_cmp_gt_i32_e32 vcc, 0, v177
	v_xor_b32_e32 v184, -1, v176
	s_nop 0
	v_cndmask_b32_e32 v186, v183, v185, vcc
	v_cmp_gt_i32_e32 vcc, 0, v176
	s_nop 1
	v_cndmask_b32_e32 v187, v182, v184, vcc
	v_cmp_le_i32_e32 vcc, v188, v132
	s_nop 1
	v_cndmask_b32_e32 v187, 0, v187, vcc
	v_cmp_le_i32_e32 vcc, v188, v1
	v_lshl_add_u32 v189, s14, 7, v175
	s_nop 0
	v_cndmask_b32_e32 v186, 0, v186, vcc
	ds_write2st64_b32 v189, v186, v187 offset1:128
	v_lshrrev_b32_e32 v190, 20, v186
	v_cmp_eq_u32_e32 vcc, 0, v186
	v_lshrrev_b32_e32 v191, 17, v186
	v_and_b32_e32 v190, 0xffc, v190
	v_and_b32_e32 v191, 16, v191
	v_add_u32_e32 v190, v165, v190
	v_lshlrev_b32_e64 v191, v191, 1
	v_cndmask_b32_e32 v190, v190, v166, vcc
	v_cndmask_b32_e64 v191, v191, 0, vcc
	ds_add_u32 v190, v191
	v_lshrrev_b32_e32 v190, 20, v187
	v_cmp_eq_u32_e32 vcc, 0, v187
	v_lshrrev_b32_e32 v191, 17, v187
	v_and_b32_e32 v190, 0xffc, v190
	v_and_b32_e32 v191, 16, v191
	v_add3_u32 v190, v165, v190, s73
	v_lshlrev_b32_e64 v191, v191, 1
	v_cndmask_b32_e32 v190, v190, v166, vcc
	v_cndmask_b32_e64 v191, v191, 0, vcc
	ds_add_u32 v190, v191
	s_waitcnt lgkmcnt(3)
	v_readfirstlane_b32 s15, v171
	s_add_i32 s10, s10, 1
	s_cmpk_lt_i32 s10, 0x400
	s_cbranch_scc1 .Lidx_loop
	s_branch .Lidx_done

.LBB0_975:
	s_or_b64 exec, exec, s[4:5]
	v_mov_b32_e32 v15, v202
	s_add_u32 s62, s28, 0x14000000
	s_waitcnt lgkmcnt(0)
	s_barrier
	s_nop 0
	s_nop 0
	s_nop 0
	s_nop 0
	s_nop 0
	s_nop 0
	s_nop 0
	s_nop 0
	s_nop 0
	s_nop 0
	s_nop 0
	s_nop 0
	s_nop 0
	s_nop 0
	s_nop 0
	s_nop 0
	s_nop 0
	s_nop 0
	s_nop 0
	s_nop 0
	s_nop 0
	s_nop 0
	s_nop 0
	s_nop 0
	s_nop 0
	s_nop 0
	s_nop 0
	s_nop 0
	s_nop 0
	s_nop 0
	s_nop 0
	s_nop 0
	s_nop 0
	s_nop 0
	s_nop 0
	s_nop 0
	s_nop 0
	s_nop 0
	s_nop 0
	s_nop 0
	s_nop 0
	s_nop 0
	s_nop 0
	s_nop 0
	s_nop 0
	s_nop 0
	s_nop 0
	s_nop 0
	s_nop 0
	s_nop 0
	s_nop 0
	s_nop 0
	s_nop 0
	s_nop 0
	s_nop 0
	s_nop 0
	s_nop 0
	s_nop 0
	s_nop 0
	s_nop 0
	s_nop 0
	s_nop 0
	s_addc_u32 s63, s29, 0
	v_readfirstlane_b32 s4, v15
	s_ashr_i32 s4, s4, 6
	s_and_b64 s[6:7], s[46:47], exec
	s_cselect_b32 s5, 8, 1
	v_cvt_f32_ubyte0_e32 v1, s5
	v_rcp_iflag_f32_e32 v1, v1
	s_add_i32 s8, s5, -1
	s_and_b64 s[6:7], s[46:47], exec
	s_cselect_b32 s24, 3, 0
	v_mul_f32_e32 v1, 0x4f7ffffe, v1
	v_cvt_u32_f32_e32 v1, v1
	s_sub_i32 s9, 0, s5
	s_abs_i32 s7, s30
	s_lshr_b32 s6, s2, s24
	v_readfirstlane_b32 s10, v1
	s_mul_i32 s9, s9, s10
	s_mul_hi_u32 s9, s10, s9
	s_add_i32 s10, s10, s9
	s_mul_hi_u32 s9, s7, s10
	s_mul_i32 s10, s9, s5
	s_sub_i32 s7, s7, s10
	s_lshl_b32 s6, s6, 3
	s_ashr_i32 s68, s30, 31
	s_add_i32 s10, s9, 1
	s_sub_i32 s11, s7, s5
	s_cmp_ge_u32 s7, s5
	s_cselect_b32 s9, s10, s9
	s_cselect_b32 s7, s11, s7
	s_add_i32 s10, s9, 1
	s_cmp_ge_u32 s7, s5
	s_cselect_b32 s7, s10, s9
	s_xor_b32 s7, s7, s68
	s_sub_i32 s7, s7, s68
	s_lshl_b32 s25, s7, 3
	s_abs_i32 s7, s25
	v_cvt_f32_u32_e32 v1, s7
	s_add_i32 s40, s4, s6
	s_sub_i32 s6, s25, s40
	s_and_b32 s41, s8, s2
	v_rcp_iflag_f32_e32 v1, v1
	s_add_i32 s8, s6, 0x1fff
	s_sub_i32 s6, 0xffffe001, s6
	s_xor_b32 s9, s8, s25
	v_mul_f32_e32 v1, 0x4f7ffffe, v1
	v_cvt_u32_f32_e32 v1, v1
	s_max_i32 s6, s8, s6
	s_sub_i32 s8, 0, s7
	s_ashr_i32 s9, s9, 31
	v_readfirstlane_b32 s10, v1
	s_mul_i32 s8, s8, s10
	s_mul_hi_u32 s8, s10, s8
	s_add_i32 s10, s10, s8
	s_mul_hi_u32 s8, s6, s10
	s_mul_i32 s10, s8, s7
	s_sub_i32 s6, s6, s10
	s_add_i32 s10, s8, 1
	s_sub_i32 s11, s6, s7
	s_cmp_ge_u32 s6, s7
	s_cselect_b32 s8, s10, s8
	s_cselect_b32 s6, s11, s6
	s_add_i32 s10, s8, 1
	s_cmp_ge_u32 s6, s7
	s_cselect_b32 s6, s10, s8
	s_sub_i32 s5, s5, s41
	s_xor_b32 s6, s6, s9
	s_add_i32 s5, s5, 15
	s_sub_i32 s42, s6, s9
	s_lshr_b32 s5, s5, s24
	s_mul_i32 s43, s42, s5
	s_cmp_lt_i32 s43, 1
	s_mov_b32 s9, 0
	s_cbranch_scc1 .LBB0_980
	s_lshl_b32 s5, s4, 14
	s_lshl_b32 s4, s4, 10
	s_add_i32 s47, s4, 0
	s_lshr_b32 s8, s41, 2
	s_add_i32 s46, s5, 0
	s_add_i32 s47, s47, 0x20000
	s_and_b32 s10, s41, 3
	s_lshl_b64 s[4:5], s[8:9], 13
	s_ashr_i32 s6, s40, 31
	s_add_u32 s4, s4, s40
	s_addc_u32 s5, s5, s6
	s_lshl_b64 s[6:7], s[4:5], 9
	v_and_b32_e32 v14, 63, v15
	s_add_u32 s6, s44, s6
	s_addc_u32 s7, s45, s7
	v_lshlrev_b32_e32 v42, 3, v14
	global_load_dwordx2 v[2:3], v42, s[6:7]
	v_and_b32_e32 v17, 15, v15
	v_bfe_u32 v4, v15, 4, 2
	v_bfe_u32 v6, v15, 2, 2
	v_and_b32_e32 v1, 7, v15
	v_lshlrev_b32_e32 v34, 3, v15
	v_mov_b32_e32 v7, 0x1000
	v_lshrrev_b32_e32 v9, 3, v15
	v_or_b32_e32 v12, 16, v17
	v_lshl_or_b32 v6, v4, 2, v6
	v_bfe_u32 v5, v15, 3, 1
	v_and_b32_e32 v10, 1, v15
	v_bitop3_b32 v13, v4, v1, 4 bitop3:0x36
	v_bitop3_b32 v16, v4, v15, 7 bitop3:0x78
	v_and_or_b32 v7, v34, 24, v7
	v_xor_b32_e32 v9, v9, v15
	v_mul_u32_u24_e32 v21, 0x40004, v14
	v_lshrrev_b32_e32 v22, 3, v12
	v_lshlrev_b32_e32 v24, 4, v6
	v_lshlrev_b32_e32 v6, 7, v6
	s_cmpk_gt_i32 s40, 0xff
	s_movk_i32 s6, 0x60
	v_lshlrev_b32_e32 v12, 7, v12
	v_xor_b32_e32 v23, v13, v5
	v_xor_b32_e32 v5, v16, v5
	v_and_or_b32 v9, v9, 6, v10
	v_or_b32_e32 v60, 0x10000, v21
	v_or_b32_e32 v61, 0x30002, v21
	v_xor_b32_e32 v10, v13, v22
	v_xor_b32_e32 v13, v16, v22
	v_or_b32_e32 v16, 0x800, v6
	v_or_b32_e32 v6, v6, v7
	s_cselect_b64 vcc, -1, 0
	v_lshlrev_b32_e32 v11, 6, v15
	s_waitcnt vmcnt(2)
	v_lshlrev_b32_e32 v52, 4, v9
	v_add_u32_e32 v9, s47, v42
	v_lshl_or_b32 v37, v10, 4, v12
	v_bitop3_b32 v10, v24, v16, s6 bitop3:0xce
	v_bitop3_b32 v39, v24, v6, s6 bitop3:0xce
	s_mul_hi_u32 s6, s4, 0x1200
	s_mulk_i32 s5, 0x1200
	s_mulk_i32 s4, 0x1200
	s_add_i32 s6, s6, s5
	v_mov_b32_e32 v43, 0
	s_add_u32 s4, s38, s4
	v_mov_b32_e32 v8, 0x60
	v_lshlrev_b32_e32 v19, 7, v17
	s_addc_u32 s5, s39, s6
	v_lshl_or_b32 v35, v23, 4, v19
	v_lshl_or_b32 v36, v5, 4, v19
	v_and_b32_e32 v5, 0x60, v24
	v_bitop3_b32 v19, v24, 64, v8 bitop3:0x6c
	v_bitop3_b32 v8, v24, 32, v8 bitop3:0x6c
	v_bfe_u32 v18, v15, 3, 3
	v_lshl_or_b32 v38, v13, 4, v12
	v_or_b32_e32 v12, v19, v16
	v_or_b32_e32 v13, v8, v16
	v_or_b32_e32 v41, v8, v6
	v_or_b32_e32 v8, v5, v16
	s_waitcnt vmcnt(1)
	v_or_b32_e32 v56, v6, v5
	v_lshlrev_b32_e32 v16, 3, v4
	v_and_b32_e32 v4, 48, v15
	v_mov_b32_e32 v5, v43
	v_lshlrev_b32_e32 v63, 6, v18
	v_bitop3_b32 v20, v18, v15, 7 bitop3:0x78
	v_or_b32_e32 v40, v19, v6
	v_add_u32_e32 v57, v10, v7
	v_add_u32_e32 v58, v12, v7
	v_add_u32_e32 v59, v13, v7
	v_add_u32_e32 v90, v8, v7
	v_add_u32_e32 v18, s47, v63
	v_mov_b32_e32 v19, v43
	v_lshlrev_b32_e32 v44, 4, v20
	v_mov_b32_e32 v45, v43
	s_mov_b32 m0, s46
	v_mov_b32_e32 v53, v43
	v_mov_b32_e32 v64, 9
	v_xor_b32_e32 v50, 16, v44
	v_mov_b32_e32 v51, v43
	v_xor_b32_e32 v48, 32, v44
	s_waitcnt vmcnt(0)
	v_cndmask_b32_e32 v2, v60, v2, vcc
	v_cndmask_b32_e32 v3, v61, v3, vcc
	ds_write_b64 v9, v[2:3]
	v_and_b32_e32 v2, 0xc0, v11
	v_lshlrev_b32_e32 v62, 1, v2
	v_lshl_or_b32 v2, s10, 9, v62
	v_mov_b32_e32 v3, v43
	v_lshl_add_u64 v[2:3], s[4:5], 0, v[2:3]
	s_lshl_b64 s[4:5], s[8:9], 22
	s_add_u32 s6, s80, s4
	v_lshl_add_u64 v[2:3], v[2:3], 0, v[4:5]
	s_addc_u32 s7, s81, s5
	global_load_dwordx4 v[10:13], v[2:3], off
	global_load_dwordx4 v[6:9], v[2:3], off offset:64
	s_waitcnt lgkmcnt(0)
	s_add_u32 s4, s37, s4
	ds_read_b128 v[30:33], v18
	ds_read_b128 v[22:25], v18 offset:16
	ds_read_b128 v[2:5], v18 offset:32
	ds_read_b128 v[26:29], v18 offset:48
	s_addc_u32 s5, s79, s5
	s_lshl_b32 s8, s10, 7
	s_add_u32 s4, s4, s8
	s_addc_u32 s5, s5, 0
	s_waitcnt lgkmcnt(3)
	v_lshlrev_b32_e32 v18, 9, v30
	s_add_u32 s6, s6, s8
	v_and_b32_e32 v18, 0x1fffe00, v18
	s_addc_u32 s7, s7, 0
	v_lshl_add_u64 v[20:21], s[4:5], 0, v[18:19]
	s_add_i32 s48, s46, 0x1000
	v_lshl_add_u64 v[20:21], v[20:21], 0, v[44:45]
	v_lshl_add_u64 v[18:19], s[6:7], 0, v[18:19]
	global_load_lds_dwordx4 v[20:21], off
	v_lshl_add_u64 v[18:19], v[18:19], 0, v[52:53]
	s_mov_b32 m0, s48
	s_add_i32 s49, s46, 0x400
	global_load_lds_dwordx4 v[18:19], off
	v_lshlrev_b32_sdwa v18, v64, v30 dst_sel:DWORD dst_unused:UNUSED_PAD src0_sel:DWORD src1_sel:WORD_1
	v_mov_b32_e32 v19, v43
	v_lshl_add_u64 v[20:21], s[4:5], 0, v[18:19]
	v_lshl_add_u64 v[20:21], v[20:21], 0, v[50:51]
	s_mov_b32 m0, s49
	v_lshl_add_u64 v[18:19], s[6:7], 0, v[18:19]
	s_add_i32 s50, s46, 0x1400
	global_load_lds_dwordx4 v[20:21], off
	v_lshl_add_u64 v[18:19], v[18:19], 0, v[52:53]
	s_mov_b32 m0, s50
	v_mov_b32_e32 v49, v43
	global_load_lds_dwordx4 v[18:19], off
	v_lshlrev_b32_e32 v18, 9, v31
	v_and_b32_e32 v18, 0x1fffe00, v18
	v_mov_b32_e32 v19, v43
	v_lshl_add_u64 v[20:21], s[4:5], 0, v[18:19]
	s_add_i32 s51, s46, 0x800
	v_lshl_add_u64 v[20:21], v[20:21], 0, v[48:49]
	s_mov_b32 m0, s51
	v_lshl_add_u64 v[18:19], s[6:7], 0, v[18:19]
	s_add_i32 s52, s46, 0x1800
	global_load_lds_dwordx4 v[20:21], off
	v_lshl_add_u64 v[18:19], v[18:19], 0, v[52:53]
	s_mov_b32 m0, s52
	v_xor_b32_e32 v46, 48, v44
	global_load_lds_dwordx4 v[18:19], off
	v_lshlrev_b32_sdwa v18, v64, v31 dst_sel:DWORD dst_unused:UNUSED_PAD src0_sel:DWORD src1_sel:WORD_1
	v_mov_b32_e32 v19, v43
	v_lshl_add_u64 v[20:21], s[4:5], 0, v[18:19]
	v_mov_b32_e32 v47, v43
	s_add_i32 s53, s46, 0xc00
	v_lshl_add_u64 v[20:21], v[20:21], 0, v[46:47]
	s_mov_b32 m0, s53
	v_lshl_add_u64 v[18:19], s[6:7], 0, v[18:19]
	s_add_i32 s54, s46, 0x1c00
	global_load_lds_dwordx4 v[20:21], off
	v_lshl_add_u64 v[18:19], v[18:19], 0, v[52:53]
	s_mov_b32 m0, s54
	v_cmp_gt_u32_e64 s[4:5], 4, v17
	global_load_lds_dwordx4 v[18:19], off
	v_and_b32_e32 v17, 0x80, v34
	v_bfe_u32 v15, v15, 5, 1
	v_or_b32_e32 v19, 32, v17
	v_or_b32_e32 v20, 64, v17
	v_or_b32_e32 v21, 0x60, v17
	v_or_b32_e32 v30, 6, v15
	v_or_b32_e32 v82, v17, v30
	v_or_b32_e32 v84, v19, v30
	v_or_b32_e32 v86, v20, v30
	v_or_b32_e32 v88, v21, v30
	v_or_b32_e32 v30, 10, v15
	v_or_b32_e32 v18, 2, v15
	v_or_b32_e32 v98, v17, v30
	v_or_b32_e32 v100, v19, v30
	v_or_b32_e32 v102, v20, v30
	v_or_b32_e32 v104, v21, v30
	v_or_b32_e32 v30, 14, v15
	v_or_b32_e32 v66, v17, v18
	v_or_b32_e32 v68, v19, v18
	v_or_b32_e32 v70, v20, v18
	v_or_b32_e32 v72, v21, v18
	v_or_b32_e32 v18, 4, v15
	v_or_b32_e32 v106, v17, v30
	v_or_b32_e32 v108, v19, v30
	v_or_b32_e32 v110, v20, v30
	v_or_b32_e32 v112, v21, v30
	v_or_b32_e32 v30, 18, v15
	v_or_b32_e32 v81, v17, v18
	v_or_b32_e32 v83, v19, v18
	v_or_b32_e32 v85, v20, v18
	v_or_b32_e32 v87, v21, v18
	v_or_b32_e32 v18, 8, v15
	v_or_b32_e32 v114, v17, v30
	v_or_b32_e32 v116, v19, v30
	v_or_b32_e32 v118, v20, v30
	v_or_b32_e32 v120, v21, v30
	v_or_b32_e32 v30, 22, v15
	v_lshl_add_u64 v[54:55], s[44:45], 0, v[42:43]
	v_or_b32_e32 v97, v17, v18
	v_or_b32_e32 v99, v19, v18
	v_or_b32_e32 v101, v20, v18
	v_or_b32_e32 v103, v21, v18
	v_or_b32_e32 v18, 12, v15
	v_or_b32_e32 v122, v17, v30
	v_or_b32_e32 v124, v19, v30
	v_or_b32_e32 v126, v20, v30
	v_or_b32_e32 v128, v21, v30
	v_or_b32_e32 v30, 26, v15
	s_abs_i32 s45, s42
	v_or_b32_e32 v105, v17, v18
	v_or_b32_e32 v107, v19, v18
	v_or_b32_e32 v109, v20, v18
	v_or_b32_e32 v111, v21, v18
	v_or_b32_e32 v18, 16, v15
	v_or_b32_e32 v130, v17, v30
	v_or_b32_e32 v132, v19, v30
	v_or_b32_e32 v134, v20, v30
	v_or_b32_e32 v136, v21, v30
	v_cvt_f32_u32_e32 v30, s45
	v_or_b32_e32 v113, v17, v18
	v_or_b32_e32 v115, v19, v18
	v_or_b32_e32 v117, v20, v18
	v_or_b32_e32 v119, v21, v18
	v_or_b32_e32 v18, 20, v15
	v_or_b32_e32 v121, v17, v18
	v_or_b32_e32 v123, v19, v18
	v_or_b32_e32 v125, v20, v18
	v_or_b32_e32 v127, v21, v18
	v_or_b32_e32 v18, 24, v15
	v_or_b32_e32 v65, v17, v15
	v_or_b32_e32 v67, v19, v15
	v_or_b32_e32 v69, v20, v15
	v_or_b32_e32 v71, v21, v15
	v_or_b32_e32 v129, v17, v18
	v_or_b32_e32 v131, v19, v18
	v_or_b32_e32 v133, v20, v18
	v_or_b32_e32 v135, v21, v18
	v_or_b32_e32 v18, 28, v15
	v_or_b32_e32 v15, 30, v15
	v_or_b32_e32 v137, v17, v18
	v_or_b32_e32 v138, v17, v15
	v_rcp_iflag_f32_e32 v17, v30
	s_sub_i32 s8, 0, s45
	s_add_i32 s44, s46, 0x2000
	v_lshlrev_b32_e32 v1, 2, v14
	v_mul_f32_e32 v17, 0x4f7ffffe, v17
	v_cvt_u32_f32_e32 v17, v17
	s_waitcnt vmcnt(0)
	v_cndmask_b32_e64 v9, 0, v9, s[4:5]
	v_cndmask_b32_e64 v8, 0, v8, s[4:5]
	v_cndmask_b32_e64 v7, 0, v7, s[4:5]
	v_readfirstlane_b32 s10, v17
	s_mul_i32 s8, s8, s10
	s_mul_hi_u32 s8, s10, s8
	v_cndmask_b32_e64 v6, 0, v6, s[4:5]
	v_cndmask_b32_e64 v13, 0, v13, s[4:5]
	v_cndmask_b32_e64 v12, 0, v12, s[4:5]
	v_cndmask_b32_e64 v11, 0, v11, s[4:5]
	v_cndmask_b32_e64 v10, 0, v10, s[4:5]
	v_cmp_gt_u32_e64 s[6:7], 16, v14
	v_add_u32_e32 v73, s46, v56
	v_add_u32_e32 v74, s46, v90
	v_add_u32_e32 v75, s46, v41
	v_add_u32_e32 v76, s46, v59
	v_add_u32_e32 v77, s46, v40
	v_add_u32_e32 v78, s46, v58
	v_add_u32_e32 v79, s46, v39
	v_add_u32_e32 v80, s46, v57
	v_add_u32_e32 v89, s44, v56
	v_add_u32_e32 v90, s44, v90
	v_add_u32_e32 v91, s44, v41
	v_add_u32_e32 v92, s44, v59
	v_add_u32_e32 v93, s44, v40
	v_add_u32_e32 v94, s44, v58
	v_add_u32_e32 v95, s44, v39
	v_add_u32_e32 v96, s44, v57
	v_or_b32_e32 v139, v19, v18
	v_or_b32_e32 v140, v19, v15
	v_or_b32_e32 v141, v20, v18
	v_or_b32_e32 v142, v20, v15
	v_or_b32_e32 v143, v21, v18
	v_or_b32_e32 v144, v21, v15
	s_ashr_i32 s55, s42, 31
	s_add_i32 s56, s10, s8
	s_sub_i32 s57, 0, s42
	v_lshlrev_b32_e32 v56, 1, v16
	s_add_i32 s58, s46, 0x3000
	s_add_i32 s59, s46, 0x2400
	s_add_i32 s60, s46, 0x3400
	s_add_i32 s61, s46, 0x2800
	s_add_i32 s64, s46, 0x3800
	s_add_i32 s65, s46, 0x2c00
	s_add_i32 s66, s46, 0x3c00
	v_add_u32_e32 v145, s46, v36
	v_add_u32_e32 v149, s46, v35
	v_add_u32_e32 v151, s46, v38
	v_add_u32_e32 v153, s46, v37
	v_lshlrev_b32_e32 v58, 1, v14
	s_movk_i32 s67, 0x7fff
	s_mov_b32 s69, 0
	s_mov_b32 s70, 0
	s_branch .LBB0_978
